# gate-up tail and roles split by blockIdx bit 3 (tail on all 8 XCDs) on top of mix split + conversion spread
# baseline (speedup 1.0000x reference)
.LBB0_1823:
	v_readlane_b32 s0, v255, 2
	v_readlane_b32 s1, v255, 3
	s_xor_b64 s[8:9], s[0:1], -1
	v_readlane_b32 s6, v252, 2
	v_readlane_b32 s7, v252, 3
	s_cmp_le_i32 s6, s20
	s_cselect_b64 s[0:1], -1, 0
	s_cmp_lt_i32 s20, s7
	s_cselect_b64 s[6:7], -1, 0
	s_and_b64 s[0:1], s[0:1], s[6:7]
	s_andn2_b64 vcc, exec, s[0:1]
	s_cbranch_vccnz .LBB0_1925
	v_readlane_b32 s6, v252, 0
	v_readlane_b32 s10, v252, 8
	v_readlane_b32 s7, v252, 1
	v_readlane_b32 s11, v252, 9
	s_load_dword s54, s[10:11], 0x0
	s_mov_b32 s55, s80
	s_lshr_b32 s101, s55, 4
	s_lshl_b32 s101, s101, 3
	s_and_b32 s100, s55, 7
	s_or_b32 s101, s101, s100
	s_waitcnt lgkmcnt(0)
	s_mov_b32 s56, s54
	s_cmpk_lg_i32 s56, 0x100
	s_cselect_b64 s[16:17], -1, 0
	s_cmpk_eq_i32 s56, 0x100
	s_cselect_b64 s[20:21], -1, 0
	s_bfe_u32 s10, s55, 0x10003
	s_bitcmp1_b32 s55, 3
	s_cselect_b64 s[26:27], -1, 0
	s_cmp_eq_u32 s10, 0
	s_cselect_b64 s[10:11], -1, 0
	s_abs_i32 s12, s56
	v_cvt_f32_u32_e32 v0, s12
	s_sub_i32 s13, 0, s12
	s_ashr_i32 s57, s56, 31
	v_rcp_iflag_f32_e32 v0, v0
	s_nop 0
	v_mul_f32_e32 v0, 0x4f7ffffe, v0
	v_cvt_u32_f32_e32 v0, v0
	s_nop 0
	v_readfirstlane_b32 s14, v0
	s_mul_i32 s13, s13, s14
	s_mul_hi_u32 s13, s14, s13
	s_add_i32 s14, s14, s13
	s_mul_hi_u32 s13, s14, 0x580
	s_mul_i32 s14, s13, s12
	s_sub_i32 s14, 0x580, s14
	s_add_i32 s15, s13, 1
	s_sub_i32 s18, s14, s12
	s_cmp_ge_u32 s14, s12
	s_cselect_b32 s13, s15, s13
	s_cselect_b32 s14, s18, s14
	s_add_i32 s15, s13, 1
	s_cmp_ge_u32 s14, s12
	s_cselect_b32 s12, s15, s13
	s_xor_b32 s12, s12, s57
	s_sub_i32 s58, s12, s57
	s_mul_i32 s28, s58, s56
	s_and_b64 vcc, exec, s[16:17]
	s_sub_i32 s24, 0x580, s28
	s_cbranch_vccnz .LBB0_1828
	s_mov_b64 s[14:15], 0
	s_and_b64 vcc, exec, s[10:11]
	s_mov_b64 s[18:19], 0
	s_cbranch_vccz .LBB0_1829
	s_mov_b32 s12, s101
	s_cmp_lt_i32 s12, s24
	s_cbranch_scc0 .LBB0_1829
	s_lshl_b32 s10, s58, 8
	s_add_u32 s10, s10, s12
	s_mov_b64 s[18:19], -1
	s_branch .LBB0_1829

.LBB0_1837:
	s_add_u32 s6, s12, 0x26000000
	s_addc_u32 s7, s13, 0
	v_readlane_b32 s2, v255, 11
	s_add_u32 s2, s12, s2
	s_addc_u32 s10, s13, 0
	s_add_u32 s14, s2, 0x30e00000
	s_addc_u32 s15, s10, 0
	s_lshl_b64 s[4:5], s[4:5], 2
	s_add_u32 s2, s12, s4
	s_addc_u32 s4, s13, s5
	v_cndmask_b32_e64 v0, 0, 1, s[20:21]
	s_add_u32 s10, s2, 0x2fa00000
	v_cmp_ne_u32_e64 s[40:41], 1, v0
	v_cndmask_b32_e64 v0, 0, 1, s[26:27]
	s_addc_u32 s11, s4, 0
	s_andn2_b64 vcc, exec, s[20:21]
	v_cmp_ne_u32_e64 s[38:39], 1, v0
	s_cbranch_vccnz .LBB0_1847
	s_and_b64 vcc, exec, s[38:39]
	s_cbranch_vccnz .LBB0_1846
	v_readlane_b32 s2, v252, 11
	v_mbcnt_lo_u32_b32 v0, -1, 0
	v_mbcnt_hi_u32_b32 v0, -1, v0
	s_nop 1
	v_add_u32_e32 v2, s2, v0
	s_mov_b32 s2, s101
	s_cmpk_gt_u32 s2, 0x7f
	s_cbranch_scc1 .LBB0_1846
	s_sub_i32 s20, 0x7f, s2
	v_lshlrev_b32_e32 v0, 4, v2
	v_and_b32_e32 v4, 48, v2
	v_mov_b32_e32 v5, v3
	v_readlane_b32 s2, v254, 34
	v_and_b32_e32 v6, 0x3f0, v0
	v_lshl_add_u64 v[0:1], s[14:15], 0, v[4:5]
	s_lshl_b32 s2, s2, 1
	v_lshl_add_u64 v[4:5], s[12:13], 0, v[4:5]
	v_lshl_add_u64 v[0:1], v[0:1], 0, s[2:3]
	v_lshl_add_u64 v[4:5], v[4:5], 0, s[2:3]
	v_readlane_b32 s2, v254, 37
	v_and_b32_e32 v26, 15, v2
	s_mov_b64 s[4:5], 0x2f400000
	v_add_u32_e32 v28, s2, v6
	v_readlane_b32 s2, v254, 62
	v_lshrrev_b32_e32 v2, 2, v2
	v_add_u32_e32 v27, 0, v6
	v_or_b32_e32 v29, s2, v26
	v_readlane_b32 s2, v254, 33
	v_lshl_add_u64 v[20:21], v[4:5], 0, s[4:5]
	v_and_b32_e32 v30, 12, v2
	v_or_b32_e32 v31, s2, v26
	s_branch .LBB0_1842

.LBB0_1850:
	s_and_b64 vcc, exec, s[38:39]
	s_cbranch_vccnz .LBB0_1913
	v_readlane_b32 s2, v252, 11
	v_mbcnt_lo_u32_b32 v0, -1, 0
	v_mbcnt_hi_u32_b32 v0, -1, v0
	s_nop 1
	v_add_u32_e32 v2, s2, v0
	s_mov_b32 s2, s101
	s_sub_i32 s4, s2, 32
	s_cmpk_gt_u32 s4, 0x5f
	s_cbranch_scc1 .LBB0_1913
	s_sub_i32 s16, 0x17f, s2
	v_lshlrev_b32_e32 v0, 4, v2
	v_and_b32_e32 v4, 48, v2
	v_mov_b32_e32 v5, v3
	v_readlane_b32 s2, v254, 34
	v_and_b32_e32 v6, 0x3f0, v0
	v_lshl_add_u64 v[0:1], s[14:15], 0, v[4:5]
	s_lshl_b32 s2, s2, 1
	v_lshl_add_u64 v[4:5], s[12:13], 0, v[4:5]
	v_lshl_add_u64 v[0:1], v[0:1], 0, s[2:3]
	v_lshl_add_u64 v[4:5], v[4:5], 0, s[2:3]
	v_readlane_b32 s2, v254, 37
	v_and_b32_e32 v26, 15, v2
	s_mov_b64 s[4:5], 0x2f400000
	v_add_u32_e32 v28, s2, v6
	v_readlane_b32 s2, v254, 62
	v_lshrrev_b32_e32 v2, 2, v2
	v_add_u32_e32 v27, 0, v6
	v_or_b32_e32 v29, s2, v26
	v_readlane_b32 s2, v254, 33
	v_lshl_add_u64 v[20:21], v[4:5], 0, s[4:5]
	v_and_b32_e32 v30, 12, v2
	v_or_b32_e32 v31, s2, v26
	s_branch .LBB0_1854

.LBB0_1861:
	s_lshl_b32 s66, s22, 6
	s_lshl_b32 s25, s22, 13
	s_lshl_b32 s22, s23, 5
	s_and_b32 s67, s22, 0x60
	s_mov_b64 s[22:23], 0x80
	s_add_i32 m0, s47, 0x18000
	v_lshl_add_u64 v[10:11], v[10:11], 0, s[22:23]
	s_waitcnt vmcnt(2)
	s_barrier
	global_load_lds_dwordx4 v[10:11], off
	v_lshl_add_u64 v[8:9], v[8:9], 0, s[22:23]
	s_add_i32 m0, s47, 0x1a000
	s_add_i32 s68, s47, 0x8000
	s_lshl_b32 s29, s67, 7
	global_load_lds_dwordx4 v[8:9], off
	v_lshl_add_u64 v[4:5], v[4:5], 0, s[22:23]
	s_mov_b32 m0, s68
	s_add_i32 s69, s47, 0xa000
	global_load_lds_dwordx4 v[4:5], off
	v_lshl_add_u64 v[4:5], v[6:7], 0, s[22:23]
	s_add_u32 s22, s50, 0x40080
	s_mov_b32 m0, s69
	s_addc_u32 s23, s51, 0
	global_load_lds_dwordx4 v[4:5], off
	s_add_i32 m0, s47, 0x1c000
	v_lshl_add_u64 v[4:5], s[22:23], 0, v[132:133]
	global_load_lds_dwordx4 v[4:5], off
	v_lshl_add_u64 v[4:5], s[22:23], 0, v[136:137]
	s_add_i32 m0, s47, 0x1e000
	v_bfe_u32 v147, v2, 4, 2
	global_load_lds_dwordx4 v[4:5], off
	v_and_b32_e32 v145, 15, v2
	v_lshlrev_b32_e32 v4, 4, v147
	v_lshlrev_b32_e32 v2, 2, v2
	v_lshl_or_b32 v4, v145, 6, v4
	v_and_b32_e32 v2, 32, v2
	v_bitop3_b32 v5, v4, s25, v2 bitop3:0xde
	v_bitop3_b32 v149, v4, s29, v2 bitop3:0xde
	v_lshlrev_b32_e32 v2, 14, v12
	v_and_b32_e32 v2, 0xffff8000, v2
	s_cmpk_lt_u32 s2, 0x100
	v_lshl_add_u32 v2, v13, 11, v2
	v_and_b32_e32 v4, 1, v12
	s_cselect_b64 s[22:23], -1, 0
	s_mov_b32 s2, s101
	v_lshl_or_b32 v2, v4, 6, v2
	s_cmp_lt_i32 s2, s24
	v_lshl_add_u32 v138, v14, 1, v2
	v_lshlrev_b32_e32 v2, 14, v15
	s_cselect_b64 s[30:31], -1, 0
	s_ashr_i32 s70, s55, 31
	v_and_b32_e32 v2, 0xffff8000, v2
	s_waitcnt vmcnt(6)
	s_cmp_lt_i32 s59, 0
	v_lshl_add_u32 v2, v16, 11, v2
	v_and_b32_e32 v4, 1, v15
	s_cselect_b64 s[24:25], -1, 0
	s_xor_b64 s[26:27], s[26:27], -1
	v_lshl_or_b32 v2, v4, 6, v2
	s_mov_b32 s71, 0
	s_and_b64 s[26:27], s[26:27], s[30:31]
	s_add_u32 s2, s28, s2
	v_mov_b32_e32 v139, v3
	v_lshl_add_u32 v140, v17, 1, v2
	v_mov_b32_e32 v141, v3
	v_add_u32_e32 v151, 0, v5
	s_barrier
	s_branch .LBB0_1864
